# v28 + attention context items handed out by a ticket counter (dynamic tail balance)
# speedup vs baseline: 1.0067x; 1.0067x over previous
.LBB0_486:
	v_readlane_b32 s16, v255, 19
	s_add_i32 s16, s16, s2
	s_cmpk_lg_i32 s2, 0x100
	s_cbranch_scc1 .Lattn_dyn_orig
	s_cmpk_lt_i32 s16, 0xa00
	s_cbranch_scc1 .LBB0_487
	v_readlane_b32 s100, v252, 7
	s_cmp_lg_u32 s100, 0
	s_cbranch_scc1 .Lattn_dyn_wait
	v_readlane_b32 s100, v252, 16
	v_readlane_b32 s101, v252, 17
	s_sub_u32 s100, s100, 16
	s_subb_u32 s101, s101, 0
	s_load_dwordx2 s[100:101], s[100:101], 0x0
	s_lshl_b32 s16, s72, 8
	s_add_i32 s16, s16, 0x8000
	s_waitcnt lgkmcnt(0)
	s_add_u32 s100, s100, s16
	s_addc_u32 s101, s101, 0
	s_mov_b64 vcc, exec
	s_mov_b64 exec, 1
	v_mov_b32_e32 v0, 1
	v_mov_b32_e32 v1, 0x23c20
	global_atomic_add v0, v161, v0, s[100:101] sc0
	s_waitcnt vmcnt(0)
	ds_write_b32 v1, v0
	s_waitcnt lgkmcnt(0)
	s_mov_b64 exec, vcc
.Lattn_dyn_wait:
	s_barrier
	v_mov_b32_e32 v1, 0x23c20
	ds_read_b32 v0, v1
	s_waitcnt lgkmcnt(0)
	v_readfirstlane_b32 s16, v0
	s_cmpk_lt_u32 s16, 0x140
	s_cbranch_scc0 .LBB0_659
	s_cmpk_lt_u32 s16, 0x40
	s_cbranch_scc1 .Lattn_dyn_diff
	s_addk_i32 s16, 0x9c0
	s_branch .LBB0_487
.Lattn_dyn_diff:
	s_addk_i32 s16, 0xb00
	s_branch .LBB0_487

	.amdhsa_kernel _Z4mega6Params
		.amdhsa_group_segment_fixed_size 0
		.amdhsa_private_segment_fixed_size 0
		.amdhsa_kernarg_size 464
		.amdhsa_user_sgpr_count 2
		.amdhsa_user_sgpr_dispatch_ptr 0
		.amdhsa_user_sgpr_queue_ptr 0
		.amdhsa_user_sgpr_kernarg_segment_ptr 1
		.amdhsa_user_sgpr_dispatch_id 0
		.amdhsa_user_sgpr_kernarg_preload_length 0
		.amdhsa_user_sgpr_kernarg_preload_offset 0
		.amdhsa_user_sgpr_private_segment_size 0
		.amdhsa_uses_dynamic_stack 0
		.amdhsa_enable_private_segment 0
		.amdhsa_system_sgpr_workgroup_id_x 1
		.amdhsa_system_sgpr_workgroup_id_y 0
		.amdhsa_system_sgpr_workgroup_id_z 0
		.amdhsa_system_sgpr_workgroup_info 0
		.amdhsa_system_vgpr_workitem_id 0
		.amdhsa_next_free_vgpr 256
		.amdhsa_next_free_sgpr 102
		.amdhsa_accum_offset 256
		.amdhsa_reserve_vcc 1
		.amdhsa_float_round_mode_32 0
		.amdhsa_float_round_mode_16_64 0
		.amdhsa_float_denorm_mode_32 3
		.amdhsa_float_denorm_mode_16_64 3
		.amdhsa_dx10_clamp 1
		.amdhsa_ieee_mode 1
		.amdhsa_fp16_overflow 0
		.amdhsa_tg_split 0
		.amdhsa_exception_fp_ieee_invalid_op 0
		.amdhsa_exception_fp_denorm_src 0
		.amdhsa_exception_fp_ieee_div_zero 0
		.amdhsa_exception_fp_ieee_overflow 0
		.amdhsa_exception_fp_ieee_underflow 0
		.amdhsa_exception_fp_ieee_inexact 0
		.amdhsa_exception_int_div_zero 0
	.end_amdhsa_kernel

amdhsa.kernels:
  - .agpr_count:     0
    .args:
      - .offset:         0
        .size:           208
        .value_kind:     by_value
      - .offset:         208
        .size:           4
        .value_kind:     hidden_block_count_x
      - .offset:         212
        .size:           4
        .value_kind:     hidden_block_count_y
      - .offset:         216
        .size:           4
        .value_kind:     hidden_block_count_z
      - .offset:         220
        .size:           2
        .value_kind:     hidden_group_size_x
      - .offset:         222
        .size:           2
        .value_kind:     hidden_group_size_y
      - .offset:         224
        .size:           2
        .value_kind:     hidden_group_size_z
      - .offset:         226
        .size:           2
        .value_kind:     hidden_remainder_x
      - .offset:         228
        .size:           2
        .value_kind:     hidden_remainder_y
      - .offset:         230
        .size:           2
        .value_kind:     hidden_remainder_z
      - .offset:         248
        .size:           8
        .value_kind:     hidden_global_offset_x
      - .offset:         256
        .size:           8
        .value_kind:     hidden_global_offset_y
      - .offset:         264
        .size:           8
        .value_kind:     hidden_global_offset_z
      - .offset:         272
        .size:           2
        .value_kind:     hidden_grid_dims
      - .offset:         328
        .size:           4
        .value_kind:     hidden_dynamic_lds_size
    .group_segment_fixed_size: 0
    .kernarg_segment_align: 8
    .kernarg_segment_size: 464
    .language:       OpenCL C
    .language_version:
      - 2
      - 0
    .max_flat_workgroup_size: 512
    .name:           _Z4mega6Params
    .private_segment_fixed_size: 0
    .sgpr_count:     108
    .sgpr_spill_count: 233
    .symbol:         _Z4mega6Params.kd
    .uniform_work_group_size: 1
    .uses_dynamic_stack: false
    .vgpr_count:     256
    .vgpr_spill_count: 0
    .wavefront_size: 64
